# diff-attention item output stage (3 sites): the 7 serial weight loads (load, vmcnt(0), multiply, store) hoisted next to the first load into dead registers, waits relaxed to vmcnt(7) so stores and load
# speedup vs baseline: 1.0007x; 1.0007x over previous
.LBB0_746:
	v_readlane_b32 s0, v254, 63
	v_mov_b32_e32 v68, v179
	v_readlane_b32 s1, v255, 0
	s_nop 4
	global_load_dwordx4 v[64:67], v177, s[0:1] offset:48
	global_load_dwordx4 v[70:73], v177, s[0:1] offset:32
	global_load_dwordx4 v[74:77], v177, s[0:1] offset:16
	global_load_dwordx4 v[78:81], v177, s[0:1]
	global_load_dwordx4 v[82:85], v177, s[0:1] offset:176
	global_load_dwordx4 v[86:89], v177, s[0:1] offset:160
	global_load_dwordx4 v[90:93], v177, s[0:1] offset:144
	global_load_dwordx4 v[94:97], v177, s[0:1] offset:128
	global_load_dwordx4 v[98:101], v177, s[0:1] offset:304
	global_load_dwordx4 v[102:105], v177, s[0:1] offset:288
	global_load_dwordx4 v[106:109], v177, s[0:1] offset:272
	global_load_dwordx4 v[110:113], v177, s[0:1] offset:256
	global_load_dwordx4 v[114:117], v177, s[0:1] offset:432
	global_load_dwordx4 v[118:121], v177, s[0:1] offset:416
	global_load_dwordx4 v[122:125], v177, s[0:1] offset:400
	global_load_dwordx4 v[126:129], v177, s[0:1] offset:384
	v_mov_b32_e32 v159, v160
	v_ashrrev_i32_e32 v69, 1, v68
	s_lshl_b32 s96, s3, 12
	s_waitcnt vmcnt(8)
	v_fma_f32 v130, v78, v94, 0
	v_fmac_f32_e32 v130, v79, v95
	s_waitcnt vmcnt(0)
	v_fma_f32 v131, v110, v126, 0
	v_fmac_f32_e32 v130, v80, v96
	v_fmac_f32_e32 v131, v111, v127
	v_fmac_f32_e32 v130, v81, v97
	v_fmac_f32_e32 v131, v112, v128
	v_fmac_f32_e32 v130, v74, v90
	v_fmac_f32_e32 v131, v113, v129
	v_fmac_f32_e32 v130, v75, v91
	v_fmac_f32_e32 v131, v106, v122
	v_fmac_f32_e32 v130, v76, v92
	v_fmac_f32_e32 v131, v107, v123
	v_fmac_f32_e32 v130, v77, v93
	v_fmac_f32_e32 v131, v108, v124
	v_fmac_f32_e32 v130, v70, v86
	v_fmac_f32_e32 v131, v109, v125
	v_fmac_f32_e32 v130, v71, v87
	v_fmac_f32_e32 v131, v102, v118
	v_fmac_f32_e32 v130, v72, v88
	v_fmac_f32_e32 v131, v103, v119
	v_fmac_f32_e32 v130, v73, v89
	v_fmac_f32_e32 v131, v104, v120
	v_fmac_f32_e32 v130, v64, v82
	v_fmac_f32_e32 v131, v105, v121
	v_fmac_f32_e32 v130, v65, v83
	v_fmac_f32_e32 v131, v98, v114
	v_fmac_f32_e32 v130, v66, v84
	v_fmac_f32_e32 v131, v99, v115
	v_fmac_f32_e32 v130, v67, v85
	global_load_dwordx4 v[70:73], v177, s[0:1] offset:80
	global_load_dwordx4 v[74:77], v177, s[0:1] offset:64
	global_load_dwordx4 v[64:67], v177, s[0:1] offset:112
	global_load_dwordx4 v[78:81], v177, s[0:1] offset:96
	global_load_dwordx4 v[82:85], v177, s[0:1] offset:208
	global_load_dwordx4 v[86:89], v177, s[0:1] offset:192
	global_load_dwordx4 v[90:93], v177, s[0:1] offset:240
	global_load_dwordx4 v[94:97], v177, s[0:1] offset:224
	v_fmac_f32_e32 v131, v100, v116
	v_fmac_f32_e32 v131, v101, v117
	global_load_dwordx4 v[98:101], v177, s[0:1] offset:336
	global_load_dwordx4 v[102:105], v177, s[0:1] offset:320
	global_load_dwordx4 v[106:109], v177, s[0:1] offset:368
	global_load_dwordx4 v[110:113], v177, s[0:1] offset:352
	global_load_dwordx4 v[114:117], v177, s[0:1] offset:464
	global_load_dwordx4 v[118:121], v177, s[0:1] offset:448
	global_load_dwordx4 v[122:125], v177, s[0:1] offset:496
	global_load_dwordx4 v[126:129], v177, s[0:1] offset:480
	s_waitcnt vmcnt(10)
	v_fmac_f32_e32 v130, v74, v86
	v_fmac_f32_e32 v130, v75, v87
	v_fmac_f32_e32 v130, v76, v88
	s_waitcnt vmcnt(2)
	v_fmac_f32_e32 v131, v102, v118
	v_fmac_f32_e32 v131, v103, v119
	v_fmac_f32_e32 v130, v77, v89
	v_fmac_f32_e32 v131, v104, v120
	v_fmac_f32_e32 v130, v70, v82
	v_fmac_f32_e32 v131, v105, v121
	v_fmac_f32_e32 v130, v71, v83
	v_fmac_f32_e32 v131, v98, v114
	v_fmac_f32_e32 v130, v72, v84
	v_fmac_f32_e32 v131, v99, v115
	v_fmac_f32_e32 v130, v73, v85
	v_pk_mul_f32 v[70:71], v[78:79], v[94:95]
	v_fmac_f32_e32 v131, v100, v116
	v_add_f32_e32 v70, v130, v70
	v_fmac_f32_e32 v131, v101, v117
	v_add_f32_e32 v72, v70, v71
	s_waitcnt vmcnt(0)
	v_pk_mul_f32 v[70:71], v[110:111], v[126:127]
	v_pk_mul_f32 v[64:65], v[64:65], v[90:91]
	v_add_f32_e32 v70, v131, v70
	v_add_f32_e32 v73, v70, v71
	v_pk_mul_f32 v[70:71], v[80:81], v[96:97]
	s_nop 0
	v_add_f32_e32 v70, v72, v70
	v_add_f32_e32 v72, v70, v71
	v_pk_mul_f32 v[70:71], v[112:113], v[128:129]
	v_add_f32_e32 v64, v72, v64
	v_add_f32_e32 v70, v73, v70
	v_add_f32_e32 v70, v70, v71
	v_add_f32_e32 v71, v64, v65
	v_pk_mul_f32 v[64:65], v[106:107], v[122:123]
	s_nop 0
	v_add_f32_e32 v64, v70, v64
	v_add_f32_e32 v70, v64, v65
	v_pk_mul_f32 v[64:65], v[66:67], v[92:93]
	s_nop 0
	v_add_f32_e32 v64, v71, v64
	v_add_f32_e32 v66, v64, v65
	v_pk_mul_f32 v[64:65], v[108:109], v[124:125]
	s_nop 0
	v_add_f32_e32 v64, v70, v64
	v_add_f32_e32 v64, v64, v65
	v_mul_f32_e32 v65, 0x3fb8aa3b, v66
	v_mul_f32_e32 v64, 0x3fb8aa3b, v64
	v_exp_f32_e32 v65, v65
	v_exp_f32_e32 v64, v64
	s_nop 0
	v_sub_f32_e32 v64, v65, v64
	ds_bpermute_b32 v65, v231, v161
	s_waitcnt lgkmcnt(0)
	v_add_f32_e32 v65, v161, v65
	v_div_scale_f32 v66, s[0:1], v65, v65, 1.0
	v_rcp_f32_e32 v67, v66
	s_nop 0
	v_fma_f32 v70, -v66, v67, 1.0
	v_fmac_f32_e32 v67, v70, v67
	v_div_scale_f32 v70, vcc, 1.0, v65, 1.0
	v_mul_f32_e32 v71, v70, v67
	v_fma_f32 v72, -v66, v71, v70
	v_fmac_f32_e32 v71, v72, v67
	v_fma_f32 v66, -v66, v71, v70
	v_div_fmas_f32 v66, v66, v67, v71
	v_div_fixup_f32 v66, v66, v65, 1.0
	ds_bpermute_b32 v65, v231, v160
	s_waitcnt lgkmcnt(0)
	v_pk_add_f32 v[64:65], v[158:159], v[64:65]
	s_nop 0
	v_div_scale_f32 v67, s[0:1], v65, v65, v64
	v_rcp_f32_e32 v70, v67
	v_readlane_b32 s0, v255, 3
	v_readlane_b32 s1, v255, 4
	v_fma_f32 v71, -v67, v70, 1.0
	v_fmac_f32_e32 v70, v71, v70
	v_div_scale_f32 v71, vcc, v64, v65, v64
	v_mul_f32_e32 v72, v71, v70
	v_fma_f32 v73, -v67, v72, v71
	v_fmac_f32_e32 v72, v73, v70
	v_fma_f32 v67, -v67, v72, v71
	v_div_fmas_f32 v67, v67, v70, v72
	v_div_fixup_f32 v64, v67, v65, v64
	v_pk_mul_f32 v[12:13], v[12:13], v[64:65] op_sel_hi:[1,0]
	s_nop 0
	v_pk_fma_f32 v[28:29], v[28:29], v[66:67], v[12:13] op_sel_hi:[1,0,1] neg_lo:[0,0,1] neg_hi:[0,0,1]
	v_pk_mul_f32 v[12:13], v[14:15], v[64:65] op_sel_hi:[1,0]
	v_lshrrev_b32_e32 v15, 3, v68
	v_and_b32_e32 v65, 4, v15
	v_pk_fma_f32 v[12:13], v[30:31], v[66:67], v[12:13] op_sel_hi:[1,0,1] neg_lo:[0,0,1] neg_hi:[0,0,1]
	v_lshlrev_b32_e32 v67, 2, v65
	v_pk_mul_f32 v[30:31], v[34:35], v[64:65] op_sel_hi:[1,0]
	v_pk_mul_f32 v[0:1], v[0:1], v[64:65] op_sel_hi:[1,0]
	v_pk_fma_f32 v[34:35], v[50:51], v[66:67], v[30:31] op_sel_hi:[1,0,1] neg_lo:[0,0,1] neg_hi:[0,0,1]
	v_pk_mul_f32 v[30:31], v[32:33], v[64:65] op_sel_hi:[1,0]
	v_pk_mul_f32 v[2:3], v[2:3], v[64:65] op_sel_hi:[1,0]
	v_pk_fma_f32 v[48:49], v[48:49], v[66:67], v[30:31] op_sel_hi:[1,0,1] neg_lo:[0,0,1] neg_hi:[0,0,1]
	global_load_dwordx4 v[30:33], v67, s[0:1]
	global_load_dwordx4 v[78:81], v67, s[0:1] offset:32
	global_load_dwordx4 v[82:85], v67, s[0:1] offset:64
	global_load_dwordx4 v[86:89], v67, s[0:1] offset:96
	global_load_dwordx4 v[90:93], v67, s[0:1] offset:128
	global_load_dwordx4 v[94:97], v67, s[0:1] offset:160
	global_load_dwordx4 v[98:101], v67, s[0:1] offset:192
	global_load_dwordx4 v[102:105], v67, s[0:1] offset:224
	v_pk_fma_f32 v[16:17], v[16:17], v[66:67], v[0:1] op_sel_hi:[1,0,1] neg_lo:[0,0,1] neg_hi:[0,0,1]
	v_pk_mul_f32 v[0:1], v[6:7], v[64:65] op_sel_hi:[1,0]
	v_pk_mul_f32 v[74:75], v[48:49], v[48:49]
	v_pk_fma_f32 v[18:19], v[18:19], v[66:67], v[2:3] op_sel_hi:[1,0,1] neg_lo:[0,0,1] neg_hi:[0,0,1]
	v_pk_fma_f32 v[2:3], v[22:23], v[66:67], v[0:1] op_sel_hi:[1,0,1] neg_lo:[0,0,1] neg_hi:[0,0,1]
	v_pk_mul_f32 v[0:1], v[4:5], v[64:65] op_sel_hi:[1,0]
	v_pk_mul_f32 v[4:5], v[8:9], v[64:65] op_sel_hi:[1,0]
	v_pk_mul_f32 v[50:51], v[34:35], v[34:35]
	v_pk_mul_f32 v[36:37], v[36:37], v[64:65] op_sel_hi:[1,0]
	v_pk_fma_f32 v[4:5], v[24:25], v[66:67], v[4:5] op_sel_hi:[1,0,1] neg_lo:[0,0,1] neg_hi:[0,0,1]
	v_add_f32_e32 v24, v74, v75
	v_pk_fma_f32 v[36:37], v[52:53], v[66:67], v[36:37] op_sel_hi:[1,0,1] neg_lo:[0,0,1] neg_hi:[0,0,1]
	v_add_f32_e32 v24, v50, v24
	v_pk_mul_f32 v[38:39], v[38:39], v[64:65] op_sel_hi:[1,0]
	v_pk_mul_f32 v[52:53], v[36:37], v[36:37]
	v_add_f32_e32 v24, v51, v24
	v_pk_fma_f32 v[38:39], v[54:55], v[66:67], v[38:39] op_sel_hi:[1,0,1] neg_lo:[0,0,1] neg_hi:[0,0,1]
	v_add_f32_e32 v24, v52, v24
	v_pk_mul_f32 v[54:55], v[38:39], v[38:39]
	v_pk_mul_f32 v[40:41], v[40:41], v[64:65] op_sel_hi:[1,0]
	v_add_f32_e32 v24, v53, v24
	v_pk_fma_f32 v[40:41], v[56:57], v[66:67], v[40:41] op_sel_hi:[1,0,1] neg_lo:[0,0,1] neg_hi:[0,0,1]
	v_add_f32_e32 v24, v54, v24
	v_pk_mul_f32 v[42:43], v[42:43], v[64:65] op_sel_hi:[1,0]
	v_pk_mul_f32 v[56:57], v[40:41], v[40:41]
	v_add_f32_e32 v24, v55, v24
	v_pk_fma_f32 v[42:43], v[58:59], v[66:67], v[42:43] op_sel_hi:[1,0,1] neg_lo:[0,0,1] neg_hi:[0,0,1]
	v_add_f32_e32 v24, v56, v24
	v_pk_mul_f32 v[58:59], v[42:43], v[42:43]
	v_pk_mul_f32 v[44:45], v[44:45], v[64:65] op_sel_hi:[1,0]
	v_add_f32_e32 v24, v57, v24
	v_pk_fma_f32 v[44:45], v[60:61], v[66:67], v[44:45] op_sel_hi:[1,0,1] neg_lo:[0,0,1] neg_hi:[0,0,1]
	v_add_f32_e32 v24, v58, v24
	v_pk_mul_f32 v[46:47], v[46:47], v[64:65] op_sel_hi:[1,0]
	v_pk_mul_f32 v[60:61], v[44:45], v[44:45]
	v_add_f32_e32 v24, v59, v24
	v_pk_fma_f32 v[46:47], v[62:63], v[66:67], v[46:47] op_sel_hi:[1,0,1] neg_lo:[0,0,1] neg_hi:[0,0,1]
	v_add_f32_e32 v24, v60, v24
	v_pk_mul_f32 v[62:63], v[46:47], v[46:47]
	v_add_f32_e32 v24, v61, v24
	v_add_f32_e32 v24, v62, v24
	v_pk_mul_f32 v[76:77], v[16:17], v[16:17]
	v_add_f32_e32 v24, v63, v24
	v_lshlrev_b32_e32 v68, 4, v68
	v_add_f32_e32 v24, v76, v24
	v_add_u32_e32 v14, s6, v69
	v_and_b32_e32 v176, 0x1f0, v68
	v_pk_mul_f32 v[68:69], v[18:19], v[18:19]
	v_add_f32_e32 v24, v77, v24
	v_pk_fma_f32 v[20:21], v[20:21], v[66:67], v[0:1] op_sel_hi:[1,0,1] neg_lo:[0,0,1] neg_hi:[0,0,1]
	v_add_f32_e32 v24, v68, v24
	v_pk_mul_f32 v[22:23], v[20:21], v[20:21]
	v_add_f32_e32 v24, v69, v24
	v_add_f32_e32 v22, v22, v24
	v_pk_mul_f32 v[6:7], v[2:3], v[2:3]
	v_add_f32_e32 v22, v23, v22
	v_add_f32_e32 v6, v6, v22
	v_pk_mul_f32 v[0:1], v[10:11], v[64:65] op_sel_hi:[1,0]
	v_pk_mul_f32 v[8:9], v[4:5], v[4:5]
	v_add_f32_e32 v6, v7, v6
	v_pk_fma_f32 v[0:1], v[26:27], v[66:67], v[0:1] op_sel_hi:[1,0,1] neg_lo:[0,0,1] neg_hi:[0,0,1]
	v_add_f32_e32 v6, v8, v6
	v_pk_mul_f32 v[10:11], v[0:1], v[0:1]
	v_add_f32_e32 v6, v9, v6
	v_add_f32_e32 v6, v10, v6
	v_pk_mul_f32 v[70:71], v[28:29], v[28:29]
	v_add_f32_e32 v6, v11, v6
	v_add_f32_e32 v6, v70, v6
	v_pk_mul_f32 v[72:73], v[12:13], v[12:13]
	v_add_f32_e32 v6, v71, v6
	v_add_f32_e32 v6, v72, v6
	v_add_f32_e32 v6, v73, v6
	ds_bpermute_b32 v7, v231, v6
	v_ashrrev_i32_e32 v14, 5, v14
	v_ashrrev_i32_e32 v15, 31, v14
	v_lshlrev_b64 v[14:15], 16, v[14:15]
	v_lshl_add_u64 v[14:15], s[64:65], 0, v[14:15]
	s_waitcnt lgkmcnt(0)
	v_add_f32_e32 v6, v6, v7
	v_fmamk_f32 v6, v6, 0x3c800000, v178
	v_cmp_gt_f32_e32 vcc, s40, v6
	v_mul_f32_e32 v7, 0x4b800000, v6
	v_lshl_add_u64 v[14:15], v[14:15], 0, s[96:97]
	v_cndmask_b32_e32 v6, v6, v7, vcc
	v_rsq_f32_e32 v6, v6
	v_lshl_add_u64 v[14:15], v[14:15], 0, v[176:177]
	v_lshlrev_b32_e32 v176, 1, v65
	v_lshl_add_u64 v[14:15], v[14:15], 0, v[176:177]
	v_mul_f32_e32 v7, 0x45800000, v6
	v_cndmask_b32_e32 v6, v6, v7, vcc
	v_mul_f32_e32 v10, v174, v6
	v_pk_mul_f32 v[6:7], v[48:49], v[10:11] op_sel_hi:[1,0]
	v_pk_mul_f32 v[8:9], v[34:35], v[10:11] op_sel_hi:[1,0]
	s_waitcnt vmcnt(7)
	v_pk_mul_f32 v[6:7], v[30:31], v[6:7]
	v_pk_mul_f32 v[8:9], v[32:33], v[8:9]
	v_cvt_pk_bf16_f32 v6, v6, v7
	v_cvt_pk_bf16_f32 v7, v8, v9
	global_store_dwordx2 v[14:15], v[6:7], off
	v_pk_mul_f32 v[22:23], v[36:37], v[10:11] op_sel_hi:[1,0]
	v_pk_mul_f32 v[16:17], v[16:17], v[10:11] op_sel_hi:[1,0]
	v_pk_mul_f32 v[2:3], v[2:3], v[10:11] op_sel_hi:[1,0]
	v_pk_mul_f32 v[0:1], v[0:1], v[10:11] op_sel_hi:[1,0]
	s_waitcnt vmcnt(7)
	v_pk_mul_f32 v[6:7], v[78:79], v[22:23]
	v_pk_mul_f32 v[22:23], v[38:39], v[10:11] op_sel_hi:[1,0]
	v_cvt_pk_bf16_f32 v6, v6, v7
	v_pk_mul_f32 v[8:9], v[80:81], v[22:23]
	v_pk_mul_f32 v[22:23], v[40:41], v[10:11] op_sel_hi:[1,0]
	v_cvt_pk_bf16_f32 v7, v8, v9
	global_store_dwordx2 v[14:15], v[6:7], off offset:512
	s_waitcnt vmcnt(7)
	v_pk_mul_f32 v[6:7], v[82:83], v[22:23]
	v_pk_mul_f32 v[22:23], v[42:43], v[10:11] op_sel_hi:[1,0]
	v_cvt_pk_bf16_f32 v6, v6, v7
	v_pk_mul_f32 v[8:9], v[84:85], v[22:23]
	v_pk_mul_f32 v[22:23], v[44:45], v[10:11] op_sel_hi:[1,0]
	v_cvt_pk_bf16_f32 v7, v8, v9
	global_store_dwordx2 v[14:15], v[6:7], off offset:1024
	s_waitcnt vmcnt(7)
	v_pk_mul_f32 v[6:7], v[86:87], v[22:23]
	v_pk_mul_f32 v[22:23], v[46:47], v[10:11] op_sel_hi:[1,0]
	v_cvt_pk_bf16_f32 v6, v6, v7
	v_pk_mul_f32 v[8:9], v[88:89], v[22:23]
	s_nop 0
	v_cvt_pk_bf16_f32 v7, v8, v9
	global_store_dwordx2 v[14:15], v[6:7], off offset:1536
	s_waitcnt vmcnt(7)
	v_pk_mul_f32 v[6:7], v[90:91], v[16:17]
	v_pk_mul_f32 v[16:17], v[18:19], v[10:11] op_sel_hi:[1,0]
	v_cvt_pk_bf16_f32 v6, v6, v7
	v_pk_mul_f32 v[8:9], v[92:93], v[16:17]
	v_pk_mul_f32 v[16:17], v[20:21], v[10:11] op_sel_hi:[1,0]
	v_cvt_pk_bf16_f32 v7, v8, v9
	global_store_dwordx2 v[14:15], v[6:7], off offset:2048
	s_waitcnt vmcnt(7)
	v_pk_mul_f32 v[6:7], v[94:95], v[16:17]
	v_pk_mul_f32 v[2:3], v[96:97], v[2:3]
	v_cvt_pk_bf16_f32 v6, v6, v7
	v_cvt_pk_bf16_f32 v7, v2, v3
	global_store_dwordx2 v[14:15], v[6:7], off offset:2560
	v_pk_mul_f32 v[6:7], v[4:5], v[10:11] op_sel_hi:[1,0]
	s_waitcnt vmcnt(7)
	v_pk_mul_f32 v[2:3], v[98:99], v[6:7]
	v_pk_mul_f32 v[0:1], v[100:101], v[0:1]
	v_cvt_pk_bf16_f32 v2, v2, v3
	v_cvt_pk_bf16_f32 v3, v0, v1
	global_store_dwordx2 v[14:15], v[2:3], off offset:3072
	v_pk_mul_f32 v[4:5], v[28:29], v[10:11] op_sel_hi:[1,0]
	s_waitcnt vmcnt(7)
	v_pk_mul_f32 v[0:1], v[102:103], v[4:5]
	v_pk_mul_f32 v[4:5], v[12:13], v[10:11] op_sel_hi:[1,0]
	v_cvt_pk_bf16_f32 v0, v0, v1
	v_pk_mul_f32 v[2:3], v[104:105], v[4:5]
	s_nop 0
	v_cvt_pk_bf16_f32 v1, v2, v3
	global_store_dwordx2 v[14:15], v[0:1], off offset:3584

.LBB0_766:
	v_readlane_b32 s0, v254, 63
	v_mov_b32_e32 v68, v179
	v_readlane_b32 s1, v255, 0
	s_nop 4
	global_load_dwordx4 v[64:67], v177, s[0:1] offset:48
	global_load_dwordx4 v[70:73], v177, s[0:1] offset:32
	global_load_dwordx4 v[74:77], v177, s[0:1] offset:16
	global_load_dwordx4 v[78:81], v177, s[0:1]
	global_load_dwordx4 v[82:85], v177, s[0:1] offset:176
	global_load_dwordx4 v[86:89], v177, s[0:1] offset:160
	global_load_dwordx4 v[90:93], v177, s[0:1] offset:144
	global_load_dwordx4 v[94:97], v177, s[0:1] offset:128
	global_load_dwordx4 v[98:101], v177, s[0:1] offset:304
	global_load_dwordx4 v[102:105], v177, s[0:1] offset:288
	global_load_dwordx4 v[106:109], v177, s[0:1] offset:272
	global_load_dwordx4 v[110:113], v177, s[0:1] offset:256
	global_load_dwordx4 v[114:117], v177, s[0:1] offset:432
	global_load_dwordx4 v[118:121], v177, s[0:1] offset:416
	global_load_dwordx4 v[122:125], v177, s[0:1] offset:400
	global_load_dwordx4 v[126:129], v177, s[0:1] offset:384
	v_mov_b32_e32 v159, v144
	v_ashrrev_i32_e32 v69, 1, v68
	s_lshl_b32 s96, s3, 12
	s_waitcnt vmcnt(8)
	v_fma_f32 v130, v78, v94, 0
	v_fmac_f32_e32 v130, v79, v95
	s_waitcnt vmcnt(0)
	v_fma_f32 v131, v110, v126, 0
	v_fmac_f32_e32 v130, v80, v96
	v_fmac_f32_e32 v131, v111, v127
	v_fmac_f32_e32 v130, v81, v97
	v_fmac_f32_e32 v131, v112, v128
	v_fmac_f32_e32 v130, v74, v90
	v_fmac_f32_e32 v131, v113, v129
	v_fmac_f32_e32 v130, v75, v91
	v_fmac_f32_e32 v131, v106, v122
	v_fmac_f32_e32 v130, v76, v92
	v_fmac_f32_e32 v131, v107, v123
	v_fmac_f32_e32 v130, v77, v93
	v_fmac_f32_e32 v131, v108, v124
	v_fmac_f32_e32 v130, v70, v86
	v_fmac_f32_e32 v131, v109, v125
	v_fmac_f32_e32 v130, v71, v87
	v_fmac_f32_e32 v131, v102, v118
	v_fmac_f32_e32 v130, v72, v88
	v_fmac_f32_e32 v131, v103, v119
	v_fmac_f32_e32 v130, v73, v89
	v_fmac_f32_e32 v131, v104, v120
	v_fmac_f32_e32 v130, v64, v82
	v_fmac_f32_e32 v131, v105, v121
	v_fmac_f32_e32 v130, v65, v83
	v_fmac_f32_e32 v131, v98, v114
	v_fmac_f32_e32 v130, v66, v84
	v_fmac_f32_e32 v131, v99, v115
	v_fmac_f32_e32 v130, v67, v85
	global_load_dwordx4 v[70:73], v177, s[0:1] offset:80
	global_load_dwordx4 v[74:77], v177, s[0:1] offset:64
	global_load_dwordx4 v[64:67], v177, s[0:1] offset:112
	global_load_dwordx4 v[78:81], v177, s[0:1] offset:96
	global_load_dwordx4 v[82:85], v177, s[0:1] offset:208
	global_load_dwordx4 v[86:89], v177, s[0:1] offset:192
	global_load_dwordx4 v[90:93], v177, s[0:1] offset:240
	global_load_dwordx4 v[94:97], v177, s[0:1] offset:224
	v_fmac_f32_e32 v131, v100, v116
	v_fmac_f32_e32 v131, v101, v117
	global_load_dwordx4 v[98:101], v177, s[0:1] offset:336
	global_load_dwordx4 v[102:105], v177, s[0:1] offset:320
	global_load_dwordx4 v[106:109], v177, s[0:1] offset:368
	global_load_dwordx4 v[110:113], v177, s[0:1] offset:352
	global_load_dwordx4 v[114:117], v177, s[0:1] offset:464
	global_load_dwordx4 v[118:121], v177, s[0:1] offset:448
	global_load_dwordx4 v[122:125], v177, s[0:1] offset:496
	global_load_dwordx4 v[126:129], v177, s[0:1] offset:480
	s_waitcnt vmcnt(10)
	v_fmac_f32_e32 v130, v74, v86
	v_fmac_f32_e32 v130, v75, v87
	v_fmac_f32_e32 v130, v76, v88
	s_waitcnt vmcnt(2)
	v_fmac_f32_e32 v131, v102, v118
	v_fmac_f32_e32 v131, v103, v119
	v_fmac_f32_e32 v130, v77, v89
	v_fmac_f32_e32 v131, v104, v120
	v_fmac_f32_e32 v130, v70, v82
	v_fmac_f32_e32 v131, v105, v121
	v_fmac_f32_e32 v130, v71, v83
	v_fmac_f32_e32 v131, v98, v114
	v_fmac_f32_e32 v130, v72, v84
	v_fmac_f32_e32 v131, v99, v115
	v_fmac_f32_e32 v130, v73, v85
	v_pk_mul_f32 v[70:71], v[78:79], v[94:95]
	v_fmac_f32_e32 v131, v100, v116
	v_add_f32_e32 v70, v130, v70
	v_fmac_f32_e32 v131, v101, v117
	v_add_f32_e32 v72, v70, v71
	s_waitcnt vmcnt(0)
	v_pk_mul_f32 v[70:71], v[110:111], v[126:127]
	v_pk_mul_f32 v[64:65], v[64:65], v[90:91]
	v_add_f32_e32 v70, v131, v70
	v_add_f32_e32 v73, v70, v71
	v_pk_mul_f32 v[70:71], v[80:81], v[96:97]
	s_nop 0
	v_add_f32_e32 v70, v72, v70
	v_add_f32_e32 v72, v70, v71
	v_pk_mul_f32 v[70:71], v[112:113], v[128:129]
	v_add_f32_e32 v64, v72, v64
	v_add_f32_e32 v70, v73, v70
	v_add_f32_e32 v70, v70, v71
	v_add_f32_e32 v71, v64, v65
	v_pk_mul_f32 v[64:65], v[106:107], v[122:123]
	s_nop 0
	v_add_f32_e32 v64, v70, v64
	v_add_f32_e32 v70, v64, v65
	v_pk_mul_f32 v[64:65], v[66:67], v[92:93]
	s_nop 0
	v_add_f32_e32 v64, v71, v64
	v_add_f32_e32 v66, v64, v65
	v_pk_mul_f32 v[64:65], v[108:109], v[124:125]
	s_nop 0
	v_add_f32_e32 v64, v70, v64
	v_add_f32_e32 v64, v64, v65
	v_mul_f32_e32 v65, 0x3fb8aa3b, v66
	v_mul_f32_e32 v64, 0x3fb8aa3b, v64
	v_exp_f32_e32 v65, v65
	v_exp_f32_e32 v64, v64
	s_nop 0
	v_sub_f32_e32 v64, v65, v64
	ds_bpermute_b32 v65, v231, v145
	s_waitcnt lgkmcnt(0)
	v_add_f32_e32 v65, v145, v65
	v_div_scale_f32 v66, s[0:1], v65, v65, 1.0
	v_rcp_f32_e32 v67, v66
	s_nop 0
	v_fma_f32 v70, -v66, v67, 1.0
	v_fmac_f32_e32 v67, v70, v67
	v_div_scale_f32 v70, vcc, 1.0, v65, 1.0
	v_mul_f32_e32 v71, v70, v67
	v_fma_f32 v72, -v66, v71, v70
	v_fmac_f32_e32 v71, v72, v67
	v_fma_f32 v66, -v66, v71, v70
	v_div_fmas_f32 v66, v66, v67, v71
	v_div_fixup_f32 v66, v66, v65, 1.0
	ds_bpermute_b32 v65, v231, v144
	s_waitcnt lgkmcnt(0)
	v_pk_add_f32 v[64:65], v[158:159], v[64:65]
	s_nop 0
	v_div_scale_f32 v67, s[0:1], v65, v65, v64
	v_rcp_f32_e32 v70, v67
	v_readlane_b32 s0, v255, 3
	v_readlane_b32 s1, v255, 4
	v_fma_f32 v71, -v67, v70, 1.0
	v_fmac_f32_e32 v70, v71, v70
	v_div_scale_f32 v71, vcc, v64, v65, v64
	v_mul_f32_e32 v72, v71, v70
	v_fma_f32 v73, -v67, v72, v71
	v_fmac_f32_e32 v72, v73, v70
	v_fma_f32 v67, -v67, v72, v71
	v_div_fmas_f32 v67, v67, v70, v72
	v_div_fixup_f32 v64, v67, v65, v64
	v_pk_mul_f32 v[12:13], v[12:13], v[64:65] op_sel_hi:[1,0]
	s_nop 0
	v_pk_fma_f32 v[28:29], v[28:29], v[66:67], v[12:13] op_sel_hi:[1,0,1] neg_lo:[0,0,1] neg_hi:[0,0,1]
	v_pk_mul_f32 v[12:13], v[14:15], v[64:65] op_sel_hi:[1,0]
	v_lshrrev_b32_e32 v15, 3, v68
	v_and_b32_e32 v65, 4, v15
	v_pk_fma_f32 v[12:13], v[30:31], v[66:67], v[12:13] op_sel_hi:[1,0,1] neg_lo:[0,0,1] neg_hi:[0,0,1]
	v_lshlrev_b32_e32 v67, 2, v65
	v_pk_mul_f32 v[30:31], v[34:35], v[64:65] op_sel_hi:[1,0]
	v_pk_mul_f32 v[0:1], v[0:1], v[64:65] op_sel_hi:[1,0]
	v_pk_fma_f32 v[34:35], v[50:51], v[66:67], v[30:31] op_sel_hi:[1,0,1] neg_lo:[0,0,1] neg_hi:[0,0,1]
	v_pk_mul_f32 v[30:31], v[32:33], v[64:65] op_sel_hi:[1,0]
	v_pk_mul_f32 v[2:3], v[2:3], v[64:65] op_sel_hi:[1,0]
	v_pk_fma_f32 v[48:49], v[48:49], v[66:67], v[30:31] op_sel_hi:[1,0,1] neg_lo:[0,0,1] neg_hi:[0,0,1]
	global_load_dwordx4 v[30:33], v67, s[0:1]
	global_load_dwordx4 v[78:81], v67, s[0:1] offset:32
	global_load_dwordx4 v[82:85], v67, s[0:1] offset:64
	global_load_dwordx4 v[86:89], v67, s[0:1] offset:96
	global_load_dwordx4 v[90:93], v67, s[0:1] offset:128
	global_load_dwordx4 v[94:97], v67, s[0:1] offset:160
	global_load_dwordx4 v[98:101], v67, s[0:1] offset:192
	global_load_dwordx4 v[102:105], v67, s[0:1] offset:224
	v_pk_fma_f32 v[16:17], v[16:17], v[66:67], v[0:1] op_sel_hi:[1,0,1] neg_lo:[0,0,1] neg_hi:[0,0,1]
	v_pk_mul_f32 v[0:1], v[6:7], v[64:65] op_sel_hi:[1,0]
	v_pk_mul_f32 v[74:75], v[48:49], v[48:49]
	v_pk_fma_f32 v[18:19], v[18:19], v[66:67], v[2:3] op_sel_hi:[1,0,1] neg_lo:[0,0,1] neg_hi:[0,0,1]
	v_pk_fma_f32 v[2:3], v[22:23], v[66:67], v[0:1] op_sel_hi:[1,0,1] neg_lo:[0,0,1] neg_hi:[0,0,1]
	v_pk_mul_f32 v[0:1], v[4:5], v[64:65] op_sel_hi:[1,0]
	v_pk_mul_f32 v[4:5], v[8:9], v[64:65] op_sel_hi:[1,0]
	v_pk_mul_f32 v[50:51], v[34:35], v[34:35]
	v_pk_mul_f32 v[36:37], v[36:37], v[64:65] op_sel_hi:[1,0]
	v_pk_fma_f32 v[4:5], v[24:25], v[66:67], v[4:5] op_sel_hi:[1,0,1] neg_lo:[0,0,1] neg_hi:[0,0,1]
	v_add_f32_e32 v24, v74, v75
	v_pk_fma_f32 v[36:37], v[52:53], v[66:67], v[36:37] op_sel_hi:[1,0,1] neg_lo:[0,0,1] neg_hi:[0,0,1]
	v_add_f32_e32 v24, v50, v24
	v_pk_mul_f32 v[38:39], v[38:39], v[64:65] op_sel_hi:[1,0]
	v_pk_mul_f32 v[52:53], v[36:37], v[36:37]
	v_add_f32_e32 v24, v51, v24
	v_pk_fma_f32 v[38:39], v[54:55], v[66:67], v[38:39] op_sel_hi:[1,0,1] neg_lo:[0,0,1] neg_hi:[0,0,1]
	v_add_f32_e32 v24, v52, v24
	v_pk_mul_f32 v[54:55], v[38:39], v[38:39]
	v_pk_mul_f32 v[40:41], v[40:41], v[64:65] op_sel_hi:[1,0]
	v_add_f32_e32 v24, v53, v24
	v_pk_fma_f32 v[40:41], v[56:57], v[66:67], v[40:41] op_sel_hi:[1,0,1] neg_lo:[0,0,1] neg_hi:[0,0,1]
	v_add_f32_e32 v24, v54, v24
	v_pk_mul_f32 v[42:43], v[42:43], v[64:65] op_sel_hi:[1,0]
	v_pk_mul_f32 v[56:57], v[40:41], v[40:41]
	v_add_f32_e32 v24, v55, v24
	v_pk_fma_f32 v[42:43], v[58:59], v[66:67], v[42:43] op_sel_hi:[1,0,1] neg_lo:[0,0,1] neg_hi:[0,0,1]
	v_add_f32_e32 v24, v56, v24
	v_pk_mul_f32 v[58:59], v[42:43], v[42:43]
	v_pk_mul_f32 v[44:45], v[44:45], v[64:65] op_sel_hi:[1,0]
	v_add_f32_e32 v24, v57, v24
	v_pk_fma_f32 v[44:45], v[60:61], v[66:67], v[44:45] op_sel_hi:[1,0,1] neg_lo:[0,0,1] neg_hi:[0,0,1]
	v_add_f32_e32 v24, v58, v24
	v_pk_mul_f32 v[46:47], v[46:47], v[64:65] op_sel_hi:[1,0]
	v_pk_mul_f32 v[60:61], v[44:45], v[44:45]
	v_add_f32_e32 v24, v59, v24
	v_pk_fma_f32 v[46:47], v[62:63], v[66:67], v[46:47] op_sel_hi:[1,0,1] neg_lo:[0,0,1] neg_hi:[0,0,1]
	v_add_f32_e32 v24, v60, v24
	v_pk_mul_f32 v[62:63], v[46:47], v[46:47]
	v_add_f32_e32 v24, v61, v24
	v_add_f32_e32 v24, v62, v24
	v_pk_mul_f32 v[76:77], v[16:17], v[16:17]
	v_add_f32_e32 v24, v63, v24
	v_lshlrev_b32_e32 v68, 4, v68
	v_add_f32_e32 v24, v76, v24
	v_add_u32_e32 v14, s6, v69
	v_and_b32_e32 v176, 0x1f0, v68
	v_pk_mul_f32 v[68:69], v[18:19], v[18:19]
	v_add_f32_e32 v24, v77, v24
	v_pk_fma_f32 v[20:21], v[20:21], v[66:67], v[0:1] op_sel_hi:[1,0,1] neg_lo:[0,0,1] neg_hi:[0,0,1]
	v_add_f32_e32 v24, v68, v24
	v_pk_mul_f32 v[22:23], v[20:21], v[20:21]
	v_add_f32_e32 v24, v69, v24
	v_add_f32_e32 v22, v22, v24
	v_pk_mul_f32 v[6:7], v[2:3], v[2:3]
	v_add_f32_e32 v22, v23, v22
	v_add_f32_e32 v6, v6, v22
	v_pk_mul_f32 v[0:1], v[10:11], v[64:65] op_sel_hi:[1,0]
	v_pk_mul_f32 v[8:9], v[4:5], v[4:5]
	v_add_f32_e32 v6, v7, v6
	v_pk_fma_f32 v[0:1], v[26:27], v[66:67], v[0:1] op_sel_hi:[1,0,1] neg_lo:[0,0,1] neg_hi:[0,0,1]
	v_add_f32_e32 v6, v8, v6
	v_pk_mul_f32 v[10:11], v[0:1], v[0:1]
	v_add_f32_e32 v6, v9, v6
	v_add_f32_e32 v6, v10, v6
	v_pk_mul_f32 v[70:71], v[28:29], v[28:29]
	v_add_f32_e32 v6, v11, v6
	v_add_f32_e32 v6, v70, v6
	v_pk_mul_f32 v[72:73], v[12:13], v[12:13]
	v_add_f32_e32 v6, v71, v6
	v_add_f32_e32 v6, v72, v6
	v_add_f32_e32 v6, v73, v6
	ds_bpermute_b32 v7, v231, v6
	v_ashrrev_i32_e32 v14, 5, v14
	v_ashrrev_i32_e32 v15, 31, v14
	v_lshlrev_b64 v[14:15], 16, v[14:15]
	v_lshl_add_u64 v[14:15], s[64:65], 0, v[14:15]
	s_waitcnt lgkmcnt(0)
	v_add_f32_e32 v6, v6, v7
	v_fmamk_f32 v6, v6, 0x3c800000, v178
	v_cmp_gt_f32_e32 vcc, s40, v6
	v_mul_f32_e32 v7, 0x4b800000, v6
	v_lshl_add_u64 v[14:15], v[14:15], 0, s[96:97]
	v_cndmask_b32_e32 v6, v6, v7, vcc
	v_rsq_f32_e32 v6, v6
	v_lshl_add_u64 v[14:15], v[14:15], 0, v[176:177]
	v_lshlrev_b32_e32 v176, 1, v65
	v_lshl_add_u64 v[14:15], v[14:15], 0, v[176:177]
	v_mul_f32_e32 v7, 0x45800000, v6
	v_cndmask_b32_e32 v6, v6, v7, vcc
	v_mul_f32_e32 v10, v174, v6
	v_pk_mul_f32 v[6:7], v[48:49], v[10:11] op_sel_hi:[1,0]
	v_pk_mul_f32 v[8:9], v[34:35], v[10:11] op_sel_hi:[1,0]
	s_waitcnt vmcnt(7)
	v_pk_mul_f32 v[6:7], v[30:31], v[6:7]
	v_pk_mul_f32 v[8:9], v[32:33], v[8:9]
	v_cvt_pk_bf16_f32 v6, v6, v7
	v_cvt_pk_bf16_f32 v7, v8, v9
	global_store_dwordx2 v[14:15], v[6:7], off
	v_pk_mul_f32 v[22:23], v[36:37], v[10:11] op_sel_hi:[1,0]
	v_pk_mul_f32 v[16:17], v[16:17], v[10:11] op_sel_hi:[1,0]
	v_pk_mul_f32 v[2:3], v[2:3], v[10:11] op_sel_hi:[1,0]
	v_pk_mul_f32 v[0:1], v[0:1], v[10:11] op_sel_hi:[1,0]
	s_waitcnt vmcnt(7)
	v_pk_mul_f32 v[6:7], v[78:79], v[22:23]
	v_pk_mul_f32 v[22:23], v[38:39], v[10:11] op_sel_hi:[1,0]
	v_cvt_pk_bf16_f32 v6, v6, v7
	v_pk_mul_f32 v[8:9], v[80:81], v[22:23]
	v_pk_mul_f32 v[22:23], v[40:41], v[10:11] op_sel_hi:[1,0]
	v_cvt_pk_bf16_f32 v7, v8, v9
	global_store_dwordx2 v[14:15], v[6:7], off offset:512
	s_waitcnt vmcnt(7)
	v_pk_mul_f32 v[6:7], v[82:83], v[22:23]
	v_pk_mul_f32 v[22:23], v[42:43], v[10:11] op_sel_hi:[1,0]
	v_cvt_pk_bf16_f32 v6, v6, v7
	v_pk_mul_f32 v[8:9], v[84:85], v[22:23]
	v_pk_mul_f32 v[22:23], v[44:45], v[10:11] op_sel_hi:[1,0]
	v_cvt_pk_bf16_f32 v7, v8, v9
	global_store_dwordx2 v[14:15], v[6:7], off offset:1024
	s_waitcnt vmcnt(7)
	v_pk_mul_f32 v[6:7], v[86:87], v[22:23]
	v_pk_mul_f32 v[22:23], v[46:47], v[10:11] op_sel_hi:[1,0]
	v_cvt_pk_bf16_f32 v6, v6, v7
	v_pk_mul_f32 v[8:9], v[88:89], v[22:23]
	s_nop 0
	v_cvt_pk_bf16_f32 v7, v8, v9
	global_store_dwordx2 v[14:15], v[6:7], off offset:1536
	s_waitcnt vmcnt(7)
	v_pk_mul_f32 v[6:7], v[90:91], v[16:17]
	v_pk_mul_f32 v[16:17], v[18:19], v[10:11] op_sel_hi:[1,0]
	v_cvt_pk_bf16_f32 v6, v6, v7
	v_pk_mul_f32 v[8:9], v[92:93], v[16:17]
	v_pk_mul_f32 v[16:17], v[20:21], v[10:11] op_sel_hi:[1,0]
	v_cvt_pk_bf16_f32 v7, v8, v9
	global_store_dwordx2 v[14:15], v[6:7], off offset:2048
	s_waitcnt vmcnt(7)
	v_pk_mul_f32 v[6:7], v[94:95], v[16:17]
	v_pk_mul_f32 v[2:3], v[96:97], v[2:3]
	v_cvt_pk_bf16_f32 v6, v6, v7
	v_cvt_pk_bf16_f32 v7, v2, v3
	global_store_dwordx2 v[14:15], v[6:7], off offset:2560
	v_pk_mul_f32 v[6:7], v[4:5], v[10:11] op_sel_hi:[1,0]
	s_waitcnt vmcnt(7)
	v_pk_mul_f32 v[2:3], v[98:99], v[6:7]
	v_pk_mul_f32 v[0:1], v[100:101], v[0:1]
	v_cvt_pk_bf16_f32 v2, v2, v3
	v_cvt_pk_bf16_f32 v3, v0, v1
	global_store_dwordx2 v[14:15], v[2:3], off offset:3072
	v_pk_mul_f32 v[4:5], v[28:29], v[10:11] op_sel_hi:[1,0]
	s_mov_b64 s[0:1], 0
	s_waitcnt vmcnt(7)
	v_pk_mul_f32 v[0:1], v[102:103], v[4:5]
	v_pk_mul_f32 v[4:5], v[12:13], v[10:11] op_sel_hi:[1,0]
	v_cvt_pk_bf16_f32 v0, v0, v1
	v_pk_mul_f32 v[2:3], v[104:105], v[4:5]
	s_nop 0
	v_cvt_pk_bf16_f32 v1, v2, v3
	global_store_dwordx2 v[14:15], v[0:1], off offset:3584
